# K-split tail units store their partial-sum slabs write-through (sc1) so the closing grid barrier's L2 write-back is short (on top of classes 1:3, peel, conv fast path)
# speedup vs baseline: 1.0014x; 1.0014x over previous
.LBB0_529:
	v_lshl_add_u32 v147, s28, 8, v1
	v_lshl_or_b32 v148, s34, 8, v143
	s_movk_i32 s0, 0x1fff
	v_cmp_lt_i32_e32 vcc, s0, v147
	v_lshlrev_b32_e32 v148, 1, v148
	s_and_saveexec_b64 s[2:3], vcc
	s_xor_b64 s[2:3], exec, s[2:3]
	s_cbranch_execz .LBB0_543
	s_lshl_b32 s0, s64, 23
	v_lshlrev_b32_e32 v147, 13, v147
	s_add_i32 s0, s0, 0xfc000000
	v_add3_u32 v147, s0, v147, v148
	v_cvt_pk_bf16_f32 v126, v126, v127
	v_cvt_pk_bf16_f32 v127, v128, v129
	v_cvt_pk_bf16_f32 v128, v122, v123
	v_cvt_pk_bf16_f32 v129, v124, v125
	buffer_store_dwordx4 v[126:129], v147, s[4:7], 0 offen sc1
	v_cvt_pk_bf16_f32 v118, v118, v119
	v_cvt_pk_bf16_f32 v119, v120, v121
	v_cvt_pk_bf16_f32 v120, v114, v115
	v_add_u32_e32 v114, 0x20000, v147
	v_cvt_pk_bf16_f32 v121, v116, v117
	buffer_store_dwordx4 v[118:121], v147, s[4:7], 0 offen offset:256 sc1
	v_cvt_pk_bf16_f32 v110, v110, v111
	v_cvt_pk_bf16_f32 v111, v112, v113
	v_cvt_pk_bf16_f32 v112, v102, v103
	v_cvt_pk_bf16_f32 v113, v104, v105
	buffer_store_dwordx4 v[110:113], v114, s[4:7], 0 offen sc1
	v_cvt_pk_bf16_f32 v102, v106, v107
	v_cvt_pk_bf16_f32 v103, v108, v109
	v_cvt_pk_bf16_f32 v104, v98, v99
	v_add_u32_e32 v98, 0x40000, v147
	v_cvt_pk_bf16_f32 v105, v100, v101
	buffer_store_dwordx4 v[102:105], v114, s[4:7], 0 offen offset:256 sc1
	v_cvt_pk_bf16_f32 v94, v94, v95
	v_cvt_pk_bf16_f32 v95, v96, v97
	v_cvt_pk_bf16_f32 v96, v86, v87
	v_cvt_pk_bf16_f32 v97, v88, v89
	buffer_store_dwordx4 v[94:97], v98, s[4:7], 0 offen sc1
	v_cvt_pk_bf16_f32 v86, v90, v91
	v_cvt_pk_bf16_f32 v87, v92, v93
	v_cvt_pk_bf16_f32 v88, v82, v83
	v_add_u32_e32 v82, 0x60000, v147
	v_cvt_pk_bf16_f32 v89, v84, v85
	buffer_store_dwordx4 v[86:89], v98, s[4:7], 0 offen offset:256 sc1
	v_cvt_pk_bf16_f32 v78, v78, v79
	v_cvt_pk_bf16_f32 v79, v80, v81
	v_cvt_pk_bf16_f32 v80, v70, v71
	v_cvt_pk_bf16_f32 v81, v72, v73
	buffer_store_dwordx4 v[78:81], v82, s[4:7], 0 offen sc1
	v_cvt_pk_bf16_f32 v70, v74, v75
	v_cvt_pk_bf16_f32 v71, v76, v77
	v_cvt_pk_bf16_f32 v72, v66, v67
	v_add_u32_e32 v66, 0x100000, v147
	v_cvt_pk_bf16_f32 v73, v68, v69
	buffer_store_dwordx4 v[70:73], v82, s[4:7], 0 offen offset:256 sc1
	v_cvt_pk_bf16_f32 v62, v62, v63
	v_cvt_pk_bf16_f32 v63, v64, v65
	v_cvt_pk_bf16_f32 v64, v54, v55
	v_cvt_pk_bf16_f32 v65, v56, v57
	buffer_store_dwordx4 v[62:65], v66, s[4:7], 0 offen sc1
	v_cvt_pk_bf16_f32 v54, v58, v59
	v_cvt_pk_bf16_f32 v55, v60, v61
	v_cvt_pk_bf16_f32 v56, v50, v51
	v_add_u32_e32 v50, 0x120000, v147
	v_cvt_pk_bf16_f32 v57, v52, v53
	buffer_store_dwordx4 v[54:57], v66, s[4:7], 0 offen offset:256 sc1
	v_cvt_pk_bf16_f32 v46, v46, v47
	v_cvt_pk_bf16_f32 v47, v48, v49
	v_cvt_pk_bf16_f32 v48, v38, v39
	v_cvt_pk_bf16_f32 v49, v40, v41
	buffer_store_dwordx4 v[46:49], v50, s[4:7], 0 offen sc1
	v_cvt_pk_bf16_f32 v38, v42, v43
	v_cvt_pk_bf16_f32 v39, v44, v45
	v_cvt_pk_bf16_f32 v40, v34, v35
	v_add_u32_e32 v34, 0x140000, v147
	v_cvt_pk_bf16_f32 v41, v36, v37
	buffer_store_dwordx4 v[38:41], v50, s[4:7], 0 offen offset:256 sc1
	v_cvt_pk_bf16_f32 v30, v30, v31
	v_cvt_pk_bf16_f32 v31, v32, v33
	v_cvt_pk_bf16_f32 v32, v22, v23
	v_cvt_pk_bf16_f32 v33, v24, v25
	buffer_store_dwordx4 v[30:33], v34, s[4:7], 0 offen sc1
	v_cvt_pk_bf16_f32 v22, v26, v27
	v_cvt_pk_bf16_f32 v23, v28, v29
	v_cvt_pk_bf16_f32 v24, v18, v19
	v_add_u32_e32 v18, 0x160000, v147
	v_cvt_pk_bf16_f32 v25, v20, v21
	buffer_store_dwordx4 v[22:25], v34, s[4:7], 0 offen offset:256 sc1
	v_cvt_pk_bf16_f32 v14, v14, v15
	v_cvt_pk_bf16_f32 v15, v16, v17
	v_cvt_pk_bf16_f32 v16, v6, v7
	v_cvt_pk_bf16_f32 v17, v8, v9
	buffer_store_dwordx4 v[14:17], v18, s[4:7], 0 offen sc1
	v_cvt_pk_bf16_f32 v6, v10, v11
	v_cvt_pk_bf16_f32 v7, v12, v13
	v_cvt_pk_bf16_f32 v8, v2, v3
	v_cvt_pk_bf16_f32 v9, v4, v5
	buffer_store_dwordx4 v[6:9], v18, s[4:7], 0 offen offset:256 sc1
	s_andn2_saveexec_b64 s[2:3], s[2:3]
	s_cbranch_execnz .LBB0_544

.LBB0_803:
	v_lshl_add_u32 v147, s28, 8, v1
	v_lshl_or_b32 v148, s30, 8, v143
	v_cmp_lt_i32_e32 vcc, s52, v147
	v_lshlrev_b32_e32 v148, 1, v148
	s_and_saveexec_b64 s[2:3], vcc
	s_xor_b64 s[2:3], exec, s[2:3]
	s_cbranch_execz .LBB0_817
	s_lshl_b32 s0, s53, 23
	v_lshlrev_b32_e32 v147, 13, v147
	s_add_i32 s0, s0, 0xfc000000
	v_add3_u32 v147, s0, v147, v148
	v_cvt_pk_bf16_f32 v126, v126, v127
	v_cvt_pk_bf16_f32 v127, v128, v129
	v_cvt_pk_bf16_f32 v128, v122, v123
	v_cvt_pk_bf16_f32 v129, v124, v125
	buffer_store_dwordx4 v[126:129], v147, s[4:7], 0 offen sc1
	v_cvt_pk_bf16_f32 v118, v118, v119
	v_cvt_pk_bf16_f32 v119, v120, v121
	v_cvt_pk_bf16_f32 v120, v114, v115
	v_add_u32_e32 v114, 0x20000, v147
	v_cvt_pk_bf16_f32 v121, v116, v117
	buffer_store_dwordx4 v[118:121], v147, s[4:7], 0 offen offset:256 sc1
	v_cvt_pk_bf16_f32 v110, v110, v111
	v_cvt_pk_bf16_f32 v111, v112, v113
	v_cvt_pk_bf16_f32 v112, v102, v103
	v_cvt_pk_bf16_f32 v113, v104, v105
	buffer_store_dwordx4 v[110:113], v114, s[4:7], 0 offen sc1
	v_cvt_pk_bf16_f32 v102, v106, v107
	v_cvt_pk_bf16_f32 v103, v108, v109
	v_cvt_pk_bf16_f32 v104, v98, v99
	v_add_u32_e32 v98, 0x40000, v147
	v_cvt_pk_bf16_f32 v105, v100, v101
	buffer_store_dwordx4 v[102:105], v114, s[4:7], 0 offen offset:256 sc1
	v_cvt_pk_bf16_f32 v94, v94, v95
	v_cvt_pk_bf16_f32 v95, v96, v97
	v_cvt_pk_bf16_f32 v96, v86, v87
	v_cvt_pk_bf16_f32 v97, v88, v89
	buffer_store_dwordx4 v[94:97], v98, s[4:7], 0 offen sc1
	v_cvt_pk_bf16_f32 v86, v90, v91
	v_cvt_pk_bf16_f32 v87, v92, v93
	v_cvt_pk_bf16_f32 v88, v82, v83
	v_add_u32_e32 v82, 0x60000, v147
	v_cvt_pk_bf16_f32 v89, v84, v85
	buffer_store_dwordx4 v[86:89], v98, s[4:7], 0 offen offset:256 sc1
	v_cvt_pk_bf16_f32 v78, v78, v79
	v_cvt_pk_bf16_f32 v79, v80, v81
	v_cvt_pk_bf16_f32 v80, v70, v71
	v_cvt_pk_bf16_f32 v81, v72, v73
	buffer_store_dwordx4 v[78:81], v82, s[4:7], 0 offen sc1
	v_cvt_pk_bf16_f32 v70, v74, v75
	v_cvt_pk_bf16_f32 v71, v76, v77
	v_cvt_pk_bf16_f32 v72, v66, v67
	v_add_u32_e32 v66, 0x100000, v147
	v_cvt_pk_bf16_f32 v73, v68, v69
	buffer_store_dwordx4 v[70:73], v82, s[4:7], 0 offen offset:256 sc1
	v_cvt_pk_bf16_f32 v62, v62, v63
	v_cvt_pk_bf16_f32 v63, v64, v65
	v_cvt_pk_bf16_f32 v64, v54, v55
	v_cvt_pk_bf16_f32 v65, v56, v57
	buffer_store_dwordx4 v[62:65], v66, s[4:7], 0 offen sc1
	v_cvt_pk_bf16_f32 v54, v58, v59
	v_cvt_pk_bf16_f32 v55, v60, v61
	v_cvt_pk_bf16_f32 v56, v50, v51
	v_add_u32_e32 v50, 0x120000, v147
	v_cvt_pk_bf16_f32 v57, v52, v53
	buffer_store_dwordx4 v[54:57], v66, s[4:7], 0 offen offset:256 sc1
	v_cvt_pk_bf16_f32 v46, v46, v47
	v_cvt_pk_bf16_f32 v47, v48, v49
	v_cvt_pk_bf16_f32 v48, v38, v39
	v_cvt_pk_bf16_f32 v49, v40, v41
	buffer_store_dwordx4 v[46:49], v50, s[4:7], 0 offen sc1
	v_cvt_pk_bf16_f32 v38, v42, v43
	v_cvt_pk_bf16_f32 v39, v44, v45
	v_cvt_pk_bf16_f32 v40, v34, v35
	v_add_u32_e32 v34, 0x140000, v147
	v_cvt_pk_bf16_f32 v41, v36, v37
	buffer_store_dwordx4 v[38:41], v50, s[4:7], 0 offen offset:256 sc1
	v_cvt_pk_bf16_f32 v30, v30, v31
	v_cvt_pk_bf16_f32 v31, v32, v33
	v_cvt_pk_bf16_f32 v32, v22, v23
	v_cvt_pk_bf16_f32 v33, v24, v25
	buffer_store_dwordx4 v[30:33], v34, s[4:7], 0 offen sc1
	v_cvt_pk_bf16_f32 v22, v26, v27
	v_cvt_pk_bf16_f32 v23, v28, v29
	v_cvt_pk_bf16_f32 v24, v18, v19
	v_add_u32_e32 v18, 0x160000, v147
	v_cvt_pk_bf16_f32 v25, v20, v21
	buffer_store_dwordx4 v[22:25], v34, s[4:7], 0 offen offset:256 sc1
	v_cvt_pk_bf16_f32 v14, v14, v15
	v_cvt_pk_bf16_f32 v15, v16, v17
	v_cvt_pk_bf16_f32 v16, v6, v7
	v_cvt_pk_bf16_f32 v17, v8, v9
	buffer_store_dwordx4 v[14:17], v18, s[4:7], 0 offen sc1
	v_cvt_pk_bf16_f32 v6, v10, v11
	v_cvt_pk_bf16_f32 v7, v12, v13
	v_cvt_pk_bf16_f32 v8, v2, v3
	v_cvt_pk_bf16_f32 v9, v4, v5
	buffer_store_dwordx4 v[6:9], v18, s[4:7], 0 offen offset:256 sc1
	s_andn2_saveexec_b64 s[2:3], s[2:3]
	s_cbranch_execnz .LBB0_818

.LBB0_964:
	s_and_b32 s2, s18, 0xf0000
	s_cmp_eq_u32 s2, 0
	s_cbranch_scc1 .LBB0_977
	v_cvt_pk_bf16_f32 v2, v156, v157
	v_cvt_pk_bf16_f32 v3, v158, v159
	v_cvt_pk_bf16_f32 v4, v148, v149
	v_cvt_pk_bf16_f32 v5, v150, v151
	buffer_store_dwordx4 v[2:5], v133, s[4:7], 0 offen sc1
	s_nop 1
	v_cvt_pk_bf16_f32 v2, v122, v123
	v_cvt_pk_bf16_f32 v3, v124, v125
	v_cvt_pk_bf16_f32 v4, v114, v115
	v_cvt_pk_bf16_f32 v5, v116, v117
	buffer_store_dwordx4 v[2:5], v165, s[4:7], 0 offen sc1
	s_nop 1
	v_cvt_pk_bf16_f32 v2, v110, v111
	v_cvt_pk_bf16_f32 v3, v112, v113
	v_cvt_pk_bf16_f32 v4, v106, v107
	v_cvt_pk_bf16_f32 v5, v108, v109
	buffer_store_dwordx4 v[2:5], v167, s[4:7], 0 offen sc1
	s_nop 1
	v_cvt_pk_bf16_f32 v2, v102, v103
	v_cvt_pk_bf16_f32 v3, v104, v105
	v_cvt_pk_bf16_f32 v4, v98, v99
	v_cvt_pk_bf16_f32 v5, v100, v101
	buffer_store_dwordx4 v[2:5], v171, s[4:7], 0 offen sc1
	s_nop 1
	v_cvt_pk_bf16_f32 v2, v162, v163
	v_cvt_pk_bf16_f32 v3, v160, v161
	v_cvt_pk_bf16_f32 v4, v154, v155
	v_cvt_pk_bf16_f32 v5, v152, v153
	buffer_store_dwordx4 v[2:5], v173, s[4:7], 0 offen sc1
	s_nop 1
	v_cvt_pk_bf16_f32 v2, v128, v129
	v_cvt_pk_bf16_f32 v3, v126, v127
	v_cvt_pk_bf16_f32 v4, v120, v121
	v_cvt_pk_bf16_f32 v5, v118, v119
	buffer_store_dwordx4 v[2:5], v174, s[4:7], 0 offen sc1
	s_nop 1
	v_cvt_pk_bf16_f32 v2, v96, v97
	v_cvt_pk_bf16_f32 v3, v94, v95
	v_cvt_pk_bf16_f32 v4, v92, v93
	v_cvt_pk_bf16_f32 v5, v90, v91
	buffer_store_dwordx4 v[2:5], v175, s[4:7], 0 offen sc1
	s_nop 1
	v_cvt_pk_bf16_f32 v2, v88, v89
	v_cvt_pk_bf16_f32 v3, v86, v87
	v_cvt_pk_bf16_f32 v4, v84, v85
	v_cvt_pk_bf16_f32 v5, v82, v83
	buffer_store_dwordx4 v[2:5], v176, s[4:7], 0 offen sc1
	s_nop 1
	v_cvt_pk_bf16_f32 v2, v74, v75
	v_cvt_pk_bf16_f32 v3, v76, v77
	v_cvt_pk_bf16_f32 v4, v66, v67
	v_cvt_pk_bf16_f32 v5, v68, v69
	buffer_store_dwordx4 v[2:5], v177, s[4:7], 0 offen sc1
	s_nop 1
	v_cvt_pk_bf16_f32 v2, v58, v59
	v_cvt_pk_bf16_f32 v3, v60, v61
	v_cvt_pk_bf16_f32 v4, v50, v51
	v_cvt_pk_bf16_f32 v5, v52, v53
	buffer_store_dwordx4 v[2:5], v178, s[4:7], 0 offen sc1
	s_nop 1
	v_cvt_pk_bf16_f32 v2, v46, v47
	v_cvt_pk_bf16_f32 v3, v48, v49
	v_cvt_pk_bf16_f32 v4, v42, v43
	v_cvt_pk_bf16_f32 v5, v44, v45
	buffer_store_dwordx4 v[2:5], v179, s[4:7], 0 offen sc1
	s_nop 1
	v_cvt_pk_bf16_f32 v2, v38, v39
	v_cvt_pk_bf16_f32 v3, v40, v41
	v_cvt_pk_bf16_f32 v4, v34, v35
	v_cvt_pk_bf16_f32 v5, v36, v37
	buffer_store_dwordx4 v[2:5], v180, s[4:7], 0 offen sc1
	s_nop 1
	v_cvt_pk_bf16_f32 v2, v80, v81
	v_cvt_pk_bf16_f32 v3, v78, v79
	v_cvt_pk_bf16_f32 v4, v72, v73
	v_cvt_pk_bf16_f32 v5, v70, v71
	buffer_store_dwordx4 v[2:5], v181, s[4:7], 0 offen sc1
	s_nop 1
	v_cvt_pk_bf16_f32 v2, v64, v65
	v_cvt_pk_bf16_f32 v3, v62, v63
	v_cvt_pk_bf16_f32 v4, v56, v57
	v_cvt_pk_bf16_f32 v5, v54, v55
	buffer_store_dwordx4 v[2:5], v182, s[4:7], 0 offen sc1
	s_nop 1
	v_cvt_pk_bf16_f32 v2, v32, v33
	v_cvt_pk_bf16_f32 v3, v30, v31
	v_cvt_pk_bf16_f32 v4, v28, v29
	v_cvt_pk_bf16_f32 v5, v26, v27
	buffer_store_dwordx4 v[2:5], v183, s[4:7], 0 offen sc1
	s_nop 1
	v_cvt_pk_bf16_f32 v2, v24, v25
	v_cvt_pk_bf16_f32 v3, v22, v23
	v_cvt_pk_bf16_f32 v4, v20, v21
	v_cvt_pk_bf16_f32 v5, v18, v19
	buffer_store_dwordx4 v[2:5], v184, s[4:7], 0 offen sc1
	s_cbranch_execnz .LBB0_967

.LBB0_1131:
	v_lshl_add_u32 v148, s50, 8, v131
	v_lshl_or_b32 v149, s51, 8, v144
	v_cmp_lt_i32_e32 vcc, s48, v148
	v_lshlrev_b32_e32 v149, 1, v149
	s_and_saveexec_b64 s[2:3], vcc
	s_xor_b64 s[2:3], exec, s[2:3]
	s_cbranch_execz .LBB0_1145
	s_lshl_b32 s18, s49, 23
	v_lshlrev_b32_e32 v148, 13, v148
	s_add_i32 s18, s18, 0xfc000000
	v_add3_u32 v148, s18, v148, v149
	v_cvt_pk_bf16_f32 v124, v124, v125
	v_cvt_pk_bf16_f32 v125, v126, v127
	v_cvt_pk_bf16_f32 v126, v120, v121
	v_cvt_pk_bf16_f32 v127, v122, v123
	buffer_store_dwordx4 v[124:127], v148, s[8:11], 0 offen sc1
	v_cvt_pk_bf16_f32 v116, v116, v117
	v_cvt_pk_bf16_f32 v117, v118, v119
	v_cvt_pk_bf16_f32 v118, v112, v113
	v_add_u32_e32 v112, 0x20000, v148
	v_cvt_pk_bf16_f32 v119, v114, v115
	buffer_store_dwordx4 v[116:119], v148, s[8:11], 0 offen offset:256 sc1
	v_cvt_pk_bf16_f32 v108, v108, v109
	v_cvt_pk_bf16_f32 v109, v110, v111
	v_cvt_pk_bf16_f32 v110, v100, v101
	v_cvt_pk_bf16_f32 v111, v102, v103
	buffer_store_dwordx4 v[108:111], v112, s[8:11], 0 offen sc1
	v_cvt_pk_bf16_f32 v100, v104, v105
	v_cvt_pk_bf16_f32 v101, v106, v107
	v_cvt_pk_bf16_f32 v102, v96, v97
	v_add_u32_e32 v96, 0x40000, v148
	v_cvt_pk_bf16_f32 v103, v98, v99
	buffer_store_dwordx4 v[100:103], v112, s[8:11], 0 offen offset:256 sc1
	v_cvt_pk_bf16_f32 v92, v92, v93
	v_cvt_pk_bf16_f32 v93, v94, v95
	v_cvt_pk_bf16_f32 v94, v84, v85
	v_cvt_pk_bf16_f32 v95, v86, v87
	buffer_store_dwordx4 v[92:95], v96, s[8:11], 0 offen sc1
	v_cvt_pk_bf16_f32 v84, v88, v89
	v_cvt_pk_bf16_f32 v85, v90, v91
	v_cvt_pk_bf16_f32 v86, v80, v81
	v_add_u32_e32 v80, 0x60000, v148
	v_cvt_pk_bf16_f32 v87, v82, v83
	buffer_store_dwordx4 v[84:87], v96, s[8:11], 0 offen offset:256 sc1
	v_cvt_pk_bf16_f32 v76, v76, v77
	v_cvt_pk_bf16_f32 v77, v78, v79
	v_cvt_pk_bf16_f32 v78, v68, v69
	v_cvt_pk_bf16_f32 v79, v70, v71
	buffer_store_dwordx4 v[76:79], v80, s[8:11], 0 offen sc1
	v_cvt_pk_bf16_f32 v68, v72, v73
	v_cvt_pk_bf16_f32 v69, v74, v75
	v_cvt_pk_bf16_f32 v70, v64, v65
	v_add_u32_e32 v64, 0x100000, v148
	v_cvt_pk_bf16_f32 v71, v66, v67
	buffer_store_dwordx4 v[68:71], v80, s[8:11], 0 offen offset:256 sc1
	v_cvt_pk_bf16_f32 v60, v60, v61
	v_cvt_pk_bf16_f32 v61, v62, v63
	v_cvt_pk_bf16_f32 v62, v52, v53
	v_cvt_pk_bf16_f32 v63, v54, v55
	buffer_store_dwordx4 v[60:63], v64, s[8:11], 0 offen sc1
	v_cvt_pk_bf16_f32 v52, v56, v57
	v_cvt_pk_bf16_f32 v53, v58, v59
	v_cvt_pk_bf16_f32 v54, v48, v49
	v_add_u32_e32 v48, 0x120000, v148
	v_cvt_pk_bf16_f32 v55, v50, v51
	buffer_store_dwordx4 v[52:55], v64, s[8:11], 0 offen offset:256 sc1
	v_cvt_pk_bf16_f32 v44, v44, v45
	v_cvt_pk_bf16_f32 v45, v46, v47
	v_cvt_pk_bf16_f32 v46, v36, v37
	v_cvt_pk_bf16_f32 v47, v38, v39
	buffer_store_dwordx4 v[44:47], v48, s[8:11], 0 offen sc1
	v_cvt_pk_bf16_f32 v36, v40, v41
	v_cvt_pk_bf16_f32 v37, v42, v43
	v_cvt_pk_bf16_f32 v38, v32, v33
	v_add_u32_e32 v32, 0x140000, v148
	v_cvt_pk_bf16_f32 v39, v34, v35
	buffer_store_dwordx4 v[36:39], v48, s[8:11], 0 offen offset:256 sc1
	v_cvt_pk_bf16_f32 v28, v28, v29
	v_cvt_pk_bf16_f32 v29, v30, v31
	v_cvt_pk_bf16_f32 v30, v20, v21
	v_cvt_pk_bf16_f32 v31, v22, v23
	buffer_store_dwordx4 v[28:31], v32, s[8:11], 0 offen sc1
	v_cvt_pk_bf16_f32 v20, v24, v25
	v_cvt_pk_bf16_f32 v21, v26, v27
	v_cvt_pk_bf16_f32 v22, v16, v17
	v_add_u32_e32 v16, 0x160000, v148
	v_cvt_pk_bf16_f32 v23, v18, v19
	buffer_store_dwordx4 v[20:23], v32, s[8:11], 0 offen offset:256 sc1
	v_cvt_pk_bf16_f32 v12, v12, v13
	v_cvt_pk_bf16_f32 v13, v14, v15
	v_cvt_pk_bf16_f32 v14, v4, v5
	v_cvt_pk_bf16_f32 v15, v6, v7
	buffer_store_dwordx4 v[12:15], v16, s[8:11], 0 offen sc1
	v_cvt_pk_bf16_f32 v4, v8, v9
	v_cvt_pk_bf16_f32 v5, v10, v11
	v_cvt_pk_bf16_f32 v6, v0, v1
	v_cvt_pk_bf16_f32 v7, v2, v3
	buffer_store_dwordx4 v[4:7], v16, s[8:11], 0 offen offset:256 sc1
	s_andn2_saveexec_b64 s[2:3], s[2:3]
	s_cbranch_execnz .LBB0_1146
